# P1 K-loop: LDS-DMA loads in SGPR-base + VGPR-offset form, 16 VALU 64-bit address adds per iteration removed from the load phases
# baseline (speedup 1.0000x reference)
.LBB0_170:
	s_add_u32 s10, s8, 0xfffc0080
	s_addc_u32 s11, s9, -1
	s_add_i32 s30, 0, 0x10000
	s_cmp_eq_u32 s29, 12
	s_cselect_b32 s13, s3, s11
	s_cselect_b32 s12, s24, s10
	v_add_u32_e32 v0, s30, v197
	s_cselect_b32 s11, s25, s28
	s_cselect_b32 s10, s26, s27
	s_add_i32 s31, 0, 0x14000
	ds_read_b128 v[130:133], v0
	ds_read_b128 v[134:137], v0 offset:1024
	ds_read_b128 v[138:141], v0 offset:2048
	ds_read_b128 v[142:145], v0 offset:3072
	v_add_u32_e32 v0, s31, v197
	ds_read_b128 v[170:173], v0
	ds_read_b128 v[174:177], v0 offset:1024
	ds_read_b128 v[202:205], v0 offset:2048
	ds_read_b128 v[206:209], v0 offset:3072
	s_add_i32 m0, s59, 0xc000
	ds_read_b128 v[210:213], v200
	ds_read_b128 v[216:219], v200 offset:1024
	ds_read_b128 v[220:223], v200 offset:2048
	ds_read_b128 v[224:227], v200 offset:3072
	ds_read_b128 v[228:231], v200 offset:4096
	ds_read_b128 v[232:235], v200 offset:5120
	ds_read_b128 v[236:239], v200 offset:6144
	ds_read_b128 v[240:243], v200 offset:7168
	global_load_lds_dwordx4 v166, s[8:9]
	s_add_i32 m0, s59, 0xe000
	s_nop 0
	global_load_lds_dwordx4 v168, s[8:9]
	s_waitcnt vmcnt(8)
	s_waitcnt lgkmcnt(0)
	s_barrier
	s_setprio 1
	s_waitcnt lgkmcnt(0)
	v_mfma_f32_16x16x32_bf16 v[126:129], v[130:133], v[210:213], v[126:129]
	v_mfma_f32_16x16x32_bf16 v[122:125], v[138:141], v[210:213], v[122:125]
	v_mfma_f32_16x16x32_bf16 v[110:113], v[130:133], v[220:223], v[110:113]
	v_mfma_f32_16x16x32_bf16 v[106:109], v[138:141], v[220:223], v[106:109]
	v_mfma_f32_16x16x32_bf16 v[94:97], v[130:133], v[228:231], v[94:97]
	v_mfma_f32_16x16x32_bf16 v[90:93], v[138:141], v[228:231], v[90:93]
	v_mfma_f32_16x16x32_bf16 v[78:81], v[130:133], v[236:239], v[78:81]
	v_mfma_f32_16x16x32_bf16 v[74:77], v[138:141], v[236:239], v[74:77]
	v_mfma_f32_16x16x32_bf16 v[126:129], v[134:137], v[216:219], v[126:129]
	v_mfma_f32_16x16x32_bf16 v[122:125], v[142:145], v[216:219], v[122:125]
	v_mfma_f32_16x16x32_bf16 v[110:113], v[134:137], v[224:227], v[110:113]
	v_mfma_f32_16x16x32_bf16 v[106:109], v[142:145], v[224:227], v[106:109]
	v_mfma_f32_16x16x32_bf16 v[94:97], v[134:137], v[232:235], v[94:97]
	v_mfma_f32_16x16x32_bf16 v[90:93], v[142:145], v[232:235], v[90:93]
	v_mfma_f32_16x16x32_bf16 v[78:81], v[134:137], v[240:243], v[78:81]
	v_mfma_f32_16x16x32_bf16 v[74:77], v[142:145], v[240:243], v[74:77]
	s_setprio 0
	s_setprio 1
	v_mfma_f32_16x16x32_bf16 v[118:121], v[170:173], v[210:213], v[118:121]
	v_mfma_f32_16x16x32_bf16 v[114:117], v[202:205], v[210:213], v[114:117]
	v_mfma_f32_16x16x32_bf16 v[102:105], v[170:173], v[220:223], v[102:105]
	v_mfma_f32_16x16x32_bf16 v[98:101], v[202:205], v[220:223], v[98:101]
	v_mfma_f32_16x16x32_bf16 v[86:89], v[170:173], v[228:231], v[86:89]
	v_mfma_f32_16x16x32_bf16 v[82:85], v[202:205], v[228:231], v[82:85]
	v_mfma_f32_16x16x32_bf16 v[70:73], v[170:173], v[236:239], v[70:73]
	v_mfma_f32_16x16x32_bf16 v[66:69], v[202:205], v[236:239], v[66:69]
	v_mfma_f32_16x16x32_bf16 v[118:121], v[174:177], v[216:219], v[118:121]
	v_mfma_f32_16x16x32_bf16 v[114:117], v[206:209], v[216:219], v[114:117]
	v_mfma_f32_16x16x32_bf16 v[102:105], v[174:177], v[224:227], v[102:105]
	v_mfma_f32_16x16x32_bf16 v[98:101], v[206:209], v[224:227], v[98:101]
	v_mfma_f32_16x16x32_bf16 v[86:89], v[174:177], v[232:235], v[86:89]
	v_mfma_f32_16x16x32_bf16 v[82:85], v[206:209], v[232:235], v[82:85]
	v_mfma_f32_16x16x32_bf16 v[70:73], v[174:177], v[240:243], v[70:73]
	v_mfma_f32_16x16x32_bf16 v[66:69], v[206:209], v[240:243], v[66:69]
	s_setprio 0
	s_barrier
	s_add_i32 s30, s30, s61
	s_mov_b32 m0, s30
	ds_read_b128 v[210:213], v200 offset:16384
	ds_read_b128 v[216:219], v200 offset:17408
	ds_read_b128 v[220:223], v200 offset:18432
	ds_read_b128 v[224:227], v200 offset:19456
	ds_read_b128 v[228:231], v200 offset:20480
	ds_read_b128 v[232:235], v200 offset:21504
	ds_read_b128 v[236:239], v200 offset:22528
	ds_read_b128 v[240:243], v200 offset:23552
	global_load_lds_dwordx4 v154, s[10:11]
	s_add_i32 m0, s30, 0x2000
	s_add_u32 s42, s10, 0x40000
	s_addc_u32 s43, s11, 0
	s_add_i32 s30, s31, s61
	global_load_lds_dwordx4 v158, s[10:11]
	s_mov_b32 m0, s30
	s_nop 0
	global_load_lds_dwordx4 v154, s[42:43]
	s_add_i32 m0, s30, 0x2000
	s_nop 0
	global_load_lds_dwordx4 v158, s[42:43]
	s_mov_b32 m0, s59
	s_nop 0
	global_load_lds_dwordx4 v152, s[12:13]
	s_mov_b32 m0, s62
	s_nop 0
	global_load_lds_dwordx4 v156, s[12:13]
	s_waitcnt vmcnt(8)
	s_waitcnt lgkmcnt(0)
	s_barrier
	s_setprio 1
	s_waitcnt lgkmcnt(0)
	v_mfma_f32_16x16x32_bf16 v[62:65], v[130:133], v[210:213], v[62:65]
	v_mfma_f32_16x16x32_bf16 v[58:61], v[138:141], v[210:213], v[58:61]
	v_mfma_f32_16x16x32_bf16 v[46:49], v[130:133], v[220:223], v[46:49]
	v_mfma_f32_16x16x32_bf16 v[42:45], v[138:141], v[220:223], v[42:45]
	v_mfma_f32_16x16x32_bf16 v[30:33], v[130:133], v[228:231], v[30:33]
	v_mfma_f32_16x16x32_bf16 v[26:29], v[138:141], v[228:231], v[26:29]
	v_mfma_f32_16x16x32_bf16 v[14:17], v[130:133], v[236:239], v[14:17]
	v_mfma_f32_16x16x32_bf16 v[10:13], v[138:141], v[236:239], v[10:13]
	v_mfma_f32_16x16x32_bf16 v[62:65], v[134:137], v[216:219], v[62:65]
	v_mfma_f32_16x16x32_bf16 v[58:61], v[142:145], v[216:219], v[58:61]
	v_mfma_f32_16x16x32_bf16 v[46:49], v[134:137], v[224:227], v[46:49]
	v_mfma_f32_16x16x32_bf16 v[42:45], v[142:145], v[224:227], v[42:45]
	v_mfma_f32_16x16x32_bf16 v[30:33], v[134:137], v[232:235], v[30:33]
	v_mfma_f32_16x16x32_bf16 v[26:29], v[142:145], v[232:235], v[26:29]
	v_mfma_f32_16x16x32_bf16 v[14:17], v[134:137], v[240:243], v[14:17]
	v_mfma_f32_16x16x32_bf16 v[10:13], v[142:145], v[240:243], v[10:13]
	s_setprio 0
	s_setprio 1
	v_mfma_f32_16x16x32_bf16 v[54:57], v[170:173], v[210:213], v[54:57]
	v_mfma_f32_16x16x32_bf16 v[50:53], v[202:205], v[210:213], v[50:53]
	v_mfma_f32_16x16x32_bf16 v[38:41], v[170:173], v[220:223], v[38:41]
	v_mfma_f32_16x16x32_bf16 v[34:37], v[202:205], v[220:223], v[34:37]
	v_mfma_f32_16x16x32_bf16 v[22:25], v[170:173], v[228:231], v[22:25]
	v_mfma_f32_16x16x32_bf16 v[18:21], v[202:205], v[228:231], v[18:21]
	v_mfma_f32_16x16x32_bf16 v[6:9], v[170:173], v[236:239], v[6:9]
	v_mfma_f32_16x16x32_bf16 v[2:5], v[202:205], v[236:239], v[2:5]
	v_mfma_f32_16x16x32_bf16 v[54:57], v[174:177], v[216:219], v[54:57]
	v_mfma_f32_16x16x32_bf16 v[50:53], v[206:209], v[216:219], v[50:53]
	v_mfma_f32_16x16x32_bf16 v[38:41], v[174:177], v[224:227], v[38:41]
	v_mfma_f32_16x16x32_bf16 v[34:37], v[206:209], v[224:227], v[34:37]
	v_mfma_f32_16x16x32_bf16 v[22:25], v[174:177], v[232:235], v[22:25]
	v_mfma_f32_16x16x32_bf16 v[18:21], v[206:209], v[232:235], v[18:21]
	v_mfma_f32_16x16x32_bf16 v[6:9], v[174:177], v[240:243], v[6:9]
	v_mfma_f32_16x16x32_bf16 v[2:5], v[206:209], v[240:243], v[2:5]
	s_setprio 0
	s_barrier
	s_add_i32 s30, 0, 0x18000
	v_add_u32_e32 v0, s30, v197
	s_add_i32 s31, 0, 0x1c000
	ds_read_b128 v[130:133], v0
	ds_read_b128 v[134:137], v0 offset:1024
	ds_read_b128 v[138:141], v0 offset:2048
	ds_read_b128 v[142:145], v0 offset:3072
	v_add_u32_e32 v0, s31, v197
	ds_read_b128 v[170:173], v0
	ds_read_b128 v[174:177], v0 offset:1024
	ds_read_b128 v[202:205], v0 offset:2048
	ds_read_b128 v[206:209], v0 offset:3072
	s_add_u32 s12, s12, 0x40000
	s_addc_u32 s13, s13, 0
	s_mov_b32 m0, s63
	ds_read_b128 v[210:213], v200 offset:32768
	ds_read_b128 v[216:219], v200 offset:33792
	ds_read_b128 v[220:223], v200 offset:34816
	ds_read_b128 v[224:227], v200 offset:35840
	ds_read_b128 v[228:231], v200 offset:36864
	ds_read_b128 v[232:235], v200 offset:37888
	ds_read_b128 v[236:239], v200 offset:38912
	ds_read_b128 v[240:243], v200 offset:39936
	global_load_lds_dwordx4 v152, s[12:13]
	s_mov_b32 m0, s64
	s_nop 0
	global_load_lds_dwordx4 v156, s[12:13]
	s_waitcnt vmcnt(8)
	s_waitcnt lgkmcnt(0)
	s_barrier
	s_setprio 1
	s_waitcnt lgkmcnt(0)
	v_mfma_f32_16x16x32_bf16 v[126:129], v[130:133], v[210:213], v[126:129]
	v_mfma_f32_16x16x32_bf16 v[122:125], v[138:141], v[210:213], v[122:125]
	v_mfma_f32_16x16x32_bf16 v[110:113], v[130:133], v[220:223], v[110:113]
	v_mfma_f32_16x16x32_bf16 v[106:109], v[138:141], v[220:223], v[106:109]
	v_mfma_f32_16x16x32_bf16 v[94:97], v[130:133], v[228:231], v[94:97]
	v_mfma_f32_16x16x32_bf16 v[90:93], v[138:141], v[228:231], v[90:93]
	v_mfma_f32_16x16x32_bf16 v[78:81], v[130:133], v[236:239], v[78:81]
	v_mfma_f32_16x16x32_bf16 v[74:77], v[138:141], v[236:239], v[74:77]
	v_mfma_f32_16x16x32_bf16 v[126:129], v[134:137], v[216:219], v[126:129]
	v_mfma_f32_16x16x32_bf16 v[122:125], v[142:145], v[216:219], v[122:125]
	v_mfma_f32_16x16x32_bf16 v[110:113], v[134:137], v[224:227], v[110:113]
	v_mfma_f32_16x16x32_bf16 v[106:109], v[142:145], v[224:227], v[106:109]
	v_mfma_f32_16x16x32_bf16 v[94:97], v[134:137], v[232:235], v[94:97]
	v_mfma_f32_16x16x32_bf16 v[90:93], v[142:145], v[232:235], v[90:93]
	v_mfma_f32_16x16x32_bf16 v[78:81], v[134:137], v[240:243], v[78:81]
	v_mfma_f32_16x16x32_bf16 v[74:77], v[142:145], v[240:243], v[74:77]
	s_setprio 0
	s_setprio 1
	v_mfma_f32_16x16x32_bf16 v[118:121], v[170:173], v[210:213], v[118:121]
	v_mfma_f32_16x16x32_bf16 v[114:117], v[202:205], v[210:213], v[114:117]
	v_mfma_f32_16x16x32_bf16 v[102:105], v[170:173], v[220:223], v[102:105]
	v_mfma_f32_16x16x32_bf16 v[98:101], v[202:205], v[220:223], v[98:101]
	v_mfma_f32_16x16x32_bf16 v[86:89], v[170:173], v[228:231], v[86:89]
	v_mfma_f32_16x16x32_bf16 v[82:85], v[202:205], v[228:231], v[82:85]
	v_mfma_f32_16x16x32_bf16 v[70:73], v[170:173], v[236:239], v[70:73]
	v_mfma_f32_16x16x32_bf16 v[66:69], v[202:205], v[236:239], v[66:69]
	v_mfma_f32_16x16x32_bf16 v[118:121], v[174:177], v[216:219], v[118:121]
	v_mfma_f32_16x16x32_bf16 v[114:117], v[206:209], v[216:219], v[114:117]
	v_mfma_f32_16x16x32_bf16 v[102:105], v[174:177], v[224:227], v[102:105]
	v_mfma_f32_16x16x32_bf16 v[98:101], v[206:209], v[224:227], v[98:101]
	v_mfma_f32_16x16x32_bf16 v[86:89], v[174:177], v[232:235], v[86:89]
	v_mfma_f32_16x16x32_bf16 v[82:85], v[206:209], v[232:235], v[82:85]
	v_mfma_f32_16x16x32_bf16 v[70:73], v[174:177], v[240:243], v[70:73]
	v_mfma_f32_16x16x32_bf16 v[66:69], v[206:209], v[240:243], v[66:69]
	s_setprio 0
	s_barrier
	s_add_i32 m0, s30, s61
	s_add_u32 s42, s10, 0x80
	s_addc_u32 s43, s11, 0
	ds_read_b128 v[210:213], v200 offset:49152
	ds_read_b128 v[216:219], v200 offset:50176
	ds_read_b128 v[220:223], v200 offset:51200
	ds_read_b128 v[224:227], v200 offset:52224
	ds_read_b128 v[228:231], v200 offset:53248
	ds_read_b128 v[232:235], v200 offset:54272
	ds_read_b128 v[236:239], v200 offset:55296
	ds_read_b128 v[240:243], v200 offset:56320
	global_load_lds_dwordx4 v154, s[42:43]
	s_add_i32 m0, m0, 0x2000
	s_add_u32 s10, s10, 0x40080
	s_addc_u32 s11, s11, 0
	global_load_lds_dwordx4 v158, s[42:43]
	s_add_i32 m0, s31, s61
	s_add_u32 s42, s12, 0xfffc0080
	s_addc_u32 s43, s13, -1
	global_load_lds_dwordx4 v154, s[10:11]
	s_add_i32 m0, m0, 0x2000
	s_nop 0
	global_load_lds_dwordx4 v158, s[10:11]
	s_mov_b32 m0, s66
	s_nop 0
	global_load_lds_dwordx4 v152, s[42:43]
	s_mov_b32 m0, s67
	s_add_i32 s12, s31, s61
	global_load_lds_dwordx4 v156, s[42:43]
	s_waitcnt vmcnt(8)
	s_waitcnt lgkmcnt(0)
	s_barrier
	s_setprio 1
	s_waitcnt lgkmcnt(0)
	v_mfma_f32_16x16x32_bf16 v[62:65], v[130:133], v[210:213], v[62:65]
	v_mfma_f32_16x16x32_bf16 v[58:61], v[138:141], v[210:213], v[58:61]
	v_mfma_f32_16x16x32_bf16 v[46:49], v[130:133], v[220:223], v[46:49]
	v_mfma_f32_16x16x32_bf16 v[42:45], v[138:141], v[220:223], v[42:45]
	v_mfma_f32_16x16x32_bf16 v[30:33], v[130:133], v[228:231], v[30:33]
	v_mfma_f32_16x16x32_bf16 v[26:29], v[138:141], v[228:231], v[26:29]
	v_mfma_f32_16x16x32_bf16 v[14:17], v[130:133], v[236:239], v[14:17]
	v_mfma_f32_16x16x32_bf16 v[10:13], v[138:141], v[236:239], v[10:13]
	v_mfma_f32_16x16x32_bf16 v[62:65], v[134:137], v[216:219], v[62:65]
	v_mfma_f32_16x16x32_bf16 v[58:61], v[142:145], v[216:219], v[58:61]
	v_mfma_f32_16x16x32_bf16 v[46:49], v[134:137], v[224:227], v[46:49]
	v_mfma_f32_16x16x32_bf16 v[42:45], v[142:145], v[224:227], v[42:45]
	v_mfma_f32_16x16x32_bf16 v[30:33], v[134:137], v[232:235], v[30:33]
	v_mfma_f32_16x16x32_bf16 v[26:29], v[142:145], v[232:235], v[26:29]
	v_mfma_f32_16x16x32_bf16 v[14:17], v[134:137], v[240:243], v[14:17]
	v_mfma_f32_16x16x32_bf16 v[10:13], v[142:145], v[240:243], v[10:13]
	s_setprio 0
	s_setprio 1
	v_mfma_f32_16x16x32_bf16 v[54:57], v[170:173], v[210:213], v[54:57]
	v_mfma_f32_16x16x32_bf16 v[50:53], v[202:205], v[210:213], v[50:53]
	v_mfma_f32_16x16x32_bf16 v[38:41], v[170:173], v[220:223], v[38:41]
	v_mfma_f32_16x16x32_bf16 v[34:37], v[202:205], v[220:223], v[34:37]
	v_mfma_f32_16x16x32_bf16 v[22:25], v[170:173], v[228:231], v[22:25]
	v_mfma_f32_16x16x32_bf16 v[18:21], v[202:205], v[228:231], v[18:21]
	v_mfma_f32_16x16x32_bf16 v[6:9], v[170:173], v[236:239], v[6:9]
	v_mfma_f32_16x16x32_bf16 v[2:5], v[202:205], v[236:239], v[2:5]
	v_mfma_f32_16x16x32_bf16 v[54:57], v[174:177], v[216:219], v[54:57]
	v_mfma_f32_16x16x32_bf16 v[50:53], v[206:209], v[216:219], v[50:53]
	v_mfma_f32_16x16x32_bf16 v[38:41], v[174:177], v[224:227], v[38:41]
	v_mfma_f32_16x16x32_bf16 v[34:37], v[206:209], v[224:227], v[34:37]
	v_mfma_f32_16x16x32_bf16 v[22:25], v[174:177], v[232:235], v[22:25]
	v_mfma_f32_16x16x32_bf16 v[18:21], v[206:209], v[232:235], v[18:21]
	v_mfma_f32_16x16x32_bf16 v[6:9], v[174:177], v[240:243], v[6:9]
	v_mfma_f32_16x16x32_bf16 v[2:5], v[206:209], v[240:243], v[2:5]
	s_setprio 0
	s_barrier
	s_add_i32 s29, s29, 2
	s_add_u32 s8, s8, 0x100
	s_addc_u32 s9, s9, 0
	s_add_u32 s27, s27, 0x100
	s_addc_u32 s28, s28, 0
	s_cmp_gt_u32 s29, 13
	s_cbranch_scc0 .LBB0_170
	s_and_b64 vcc, exec, s[46:47]
	s_cbranch_vccz .LBB0_173
	s_barrier
